# compression-MLP first GEMM (K=4096): skip the MFMA bursts of the zero-padded upper half of N
# speedup vs baseline: 1.0086x; 1.0086x over previous
.LBB0_287:
	s_add_i32 s4, s2, 2
	s_add_u32 s5, s0, 0x80
	s_addc_u32 s3, s1, 0
	s_add_i32 s10, 0, 0x12400
	v_add_u32_e32 v144, s10, v151
	ds_read_b128 v[132:135], v144
	ds_read_b128 v[136:139], v144 offset:1024
	ds_read_b128 v[140:143], v144 offset:2048
	ds_read_b128 v[164:167], v144 offset:3072
	s_cmp_eq_u32 s66, s2
	s_cselect_b32 s2, s38, s5
	s_cselect_b64 vcc, -1, 0
	s_cselect_b32 s3, s39, s3
	v_cndmask_b32_e32 v145, v131, v163, vcc
	v_cndmask_b32_e32 v144, v130, v162, vcc
	s_mov_b32 m0, s67
	v_lshl_add_u64 v[248:249], s[0:1], 0, v[160:161]
	ds_read_b128 v[168:171], v176 offset:9216
	ds_read_b128 v[172:175], v176 offset:10240
	ds_read_b128 v[180:183], v176 offset:11264
	ds_read_b128 v[184:187], v176 offset:12288
	ds_read_b128 v[188:191], v176 offset:13312
	ds_read_b128 v[192:195], v176 offset:14336
	ds_read_b128 v[210:213], v176 offset:15360
	ds_read_b128 v[214:217], v176 offset:16384
	s_add_i32 s5, 0, 0x16400
	v_add_u32_e32 v209, s5, v151
	ds_read_b128 v[218:221], v209
	ds_read_b128 v[222:225], v209 offset:1024
	ds_read_b128 v[226:229], v209 offset:2048
	ds_read_b128 v[230:233], v209 offset:3072
	global_load_lds_dwordx4 v[248:249], off
	v_lshl_add_u64 v[250:251], s[0:1], 0, v[158:159]
	s_mov_b32 m0, s73
	s_nop 0
	global_load_lds_dwordx4 v[250:251], off
	s_waitcnt vmcnt(8) lgkmcnt(0)
	s_barrier
	s_setprio 1
	v_mfma_f32_16x16x32_bf16 v[114:117], v[132:135], v[168:171], v[114:117]
	v_mfma_f32_16x16x32_bf16 v[126:129], v[140:143], v[168:171], v[126:129]
	v_mfma_f32_16x16x32_bf16 v[110:113], v[132:135], v[180:183], v[110:113]
	v_mfma_f32_16x16x32_bf16 v[106:109], v[140:143], v[180:183], v[106:109]
	v_mfma_f32_16x16x32_bf16 v[94:97], v[132:135], v[188:191], v[94:97]
	v_mfma_f32_16x16x32_bf16 v[90:93], v[140:143], v[188:191], v[90:93]
	v_mfma_f32_16x16x32_bf16 v[78:81], v[132:135], v[210:213], v[78:81]
	v_mfma_f32_16x16x32_bf16 v[74:77], v[140:143], v[210:213], v[74:77]
	v_mfma_f32_16x16x32_bf16 v[114:117], v[136:139], v[172:175], v[114:117]
	v_mfma_f32_16x16x32_bf16 v[126:129], v[164:167], v[172:175], v[126:129]
	v_mfma_f32_16x16x32_bf16 v[110:113], v[136:139], v[184:187], v[110:113]
	v_mfma_f32_16x16x32_bf16 v[106:109], v[164:167], v[184:187], v[106:109]
	v_mfma_f32_16x16x32_bf16 v[94:97], v[136:139], v[192:195], v[94:97]
	v_mfma_f32_16x16x32_bf16 v[90:93], v[164:167], v[192:195], v[90:93]
	v_mfma_f32_16x16x32_bf16 v[78:81], v[136:139], v[214:217], v[78:81]
	v_mfma_f32_16x16x32_bf16 v[74:77], v[164:167], v[214:217], v[74:77]
	s_cmp_eq_u32 s62, 64
	s_cbranch_scc1 .Lg4_skip1
	v_mfma_f32_16x16x32_bf16 v[122:125], v[218:221], v[168:171], v[122:125]
	v_mfma_f32_16x16x32_bf16 v[118:121], v[226:229], v[168:171], v[118:121]
	v_mfma_f32_16x16x32_bf16 v[102:105], v[218:221], v[180:183], v[102:105]
	v_mfma_f32_16x16x32_bf16 v[98:101], v[226:229], v[180:183], v[98:101]
	v_mfma_f32_16x16x32_bf16 v[86:89], v[218:221], v[188:191], v[86:89]
	v_mfma_f32_16x16x32_bf16 v[82:85], v[226:229], v[188:191], v[82:85]
	v_mfma_f32_16x16x32_bf16 v[70:73], v[218:221], v[210:213], v[70:73]
	v_mfma_f32_16x16x32_bf16 v[66:69], v[226:229], v[210:213], v[66:69]
	v_mfma_f32_16x16x32_bf16 v[122:125], v[222:225], v[172:175], v[122:125]
	v_mfma_f32_16x16x32_bf16 v[118:121], v[230:233], v[172:175], v[118:121]
	v_mfma_f32_16x16x32_bf16 v[102:105], v[222:225], v[184:187], v[102:105]
	v_mfma_f32_16x16x32_bf16 v[98:101], v[230:233], v[184:187], v[98:101]
	v_mfma_f32_16x16x32_bf16 v[86:89], v[222:225], v[192:195], v[86:89]
	v_mfma_f32_16x16x32_bf16 v[82:85], v[230:233], v[192:195], v[82:85]
	v_mfma_f32_16x16x32_bf16 v[70:73], v[222:225], v[214:217], v[70:73]
	v_mfma_f32_16x16x32_bf16 v[66:69], v[230:233], v[214:217], v[66:69]
.Lg4_skip1:
	s_setprio 0
	s_barrier
	ds_read_b128 v[168:171], v176 offset:26624
	ds_read_b128 v[172:175], v176 offset:27648
	ds_read_b128 v[180:183], v176 offset:28672
	ds_read_b128 v[184:187], v176 offset:29696
	ds_read_b128 v[188:191], v176 offset:30720
	ds_read_b128 v[192:195], v176 offset:31744
	ds_read_b128 v[210:213], v176 offset:25600
	ds_read_b128 v[214:217], v176 offset:32768
	s_add_i32 s10, s10, s45
	v_lshl_add_u64 v[234:235], v[144:145], 0, v[152:153]
	s_mov_b32 m0, s10
	v_lshl_add_u64 v[236:237], v[144:145], 0, v[156:157]
	global_load_lds_dwordx4 v[234:235], off
	s_add_i32 m0, s10, 0x2000
	v_lshl_add_u64 v[238:239], s[2:3], 0, v[146:147]
	global_load_lds_dwordx4 v[236:237], off
	s_mov_b32 m0, s46
	v_lshl_add_u64 v[240:241], s[2:3], 0, v[154:155]
	global_load_lds_dwordx4 v[238:239], off
	s_mov_b32 m0, s47
	v_lshl_add_u64 v[248:249], v[144:145], 0, s[22:23]
	global_load_lds_dwordx4 v[240:241], off
	s_add_i32 s5, s5, s45
	v_lshl_add_u64 v[144:145], v[248:249], 0, v[152:153]
	s_mov_b32 m0, s5
	v_lshl_add_u64 v[242:243], v[248:249], 0, v[156:157]
	global_load_lds_dwordx4 v[144:145], off
	s_add_i32 m0, s5, 0x2000
	s_nop 0
	global_load_lds_dwordx4 v[242:243], off
	s_waitcnt vmcnt(8) lgkmcnt(0)
	s_barrier
	s_setprio 1
	v_mfma_f32_16x16x32_bf16 v[62:65], v[132:135], v[210:213], v[62:65]
	v_mfma_f32_16x16x32_bf16 v[58:61], v[140:143], v[210:213], v[58:61]
	v_mfma_f32_16x16x32_bf16 v[46:49], v[132:135], v[172:175], v[46:49]
	v_mfma_f32_16x16x32_bf16 v[42:45], v[140:143], v[172:175], v[42:45]
	v_mfma_f32_16x16x32_bf16 v[30:33], v[132:135], v[184:187], v[30:33]
	v_mfma_f32_16x16x32_bf16 v[24:27], v[140:143], v[184:187], v[24:27]
	v_mfma_f32_16x16x32_bf16 v[12:15], v[132:135], v[192:195], v[12:15]
	v_mfma_f32_16x16x32_bf16 v[8:11], v[140:143], v[192:195], v[8:11]
	v_mfma_f32_16x16x32_bf16 v[62:65], v[136:139], v[168:171], v[62:65]
	v_mfma_f32_16x16x32_bf16 v[58:61], v[164:167], v[168:171], v[58:61]
	v_mfma_f32_16x16x32_bf16 v[46:49], v[136:139], v[180:183], v[46:49]
	v_mfma_f32_16x16x32_bf16 v[42:45], v[164:167], v[180:183], v[42:45]
	v_mfma_f32_16x16x32_bf16 v[30:33], v[136:139], v[188:191], v[30:33]
	v_mfma_f32_16x16x32_bf16 v[24:27], v[164:167], v[188:191], v[24:27]
	v_mfma_f32_16x16x32_bf16 v[12:15], v[136:139], v[214:217], v[12:15]
	v_mfma_f32_16x16x32_bf16 v[8:11], v[164:167], v[214:217], v[8:11]
	s_cmp_eq_u32 s62, 64
	s_cbranch_scc1 .Lg4_skip3
	v_mfma_f32_16x16x32_bf16 v[54:57], v[218:221], v[210:213], v[54:57]
	v_mfma_f32_16x16x32_bf16 v[50:53], v[226:229], v[210:213], v[50:53]
	v_mfma_f32_16x16x32_bf16 v[38:41], v[218:221], v[172:175], v[38:41]
	v_mfma_f32_16x16x32_bf16 v[34:37], v[226:229], v[172:175], v[34:37]
	v_mfma_f32_16x16x32_bf16 v[20:23], v[218:221], v[184:187], v[20:23]
	v_mfma_f32_16x16x32_bf16 v[16:19], v[226:229], v[184:187], v[16:19]
	v_mfma_f32_16x16x32_bf16 v[4:7], v[218:221], v[192:195], v[4:7]
	v_mfma_f32_16x16x32_bf16 v[0:3], v[226:229], v[192:195], v[0:3]
	v_mfma_f32_16x16x32_bf16 v[54:57], v[222:225], v[168:171], v[54:57]
	v_mfma_f32_16x16x32_bf16 v[50:53], v[230:233], v[168:171], v[50:53]
	v_mfma_f32_16x16x32_bf16 v[38:41], v[222:225], v[180:183], v[38:41]
	v_mfma_f32_16x16x32_bf16 v[34:37], v[230:233], v[180:183], v[34:37]
	v_mfma_f32_16x16x32_bf16 v[20:23], v[222:225], v[188:191], v[20:23]
	v_mfma_f32_16x16x32_bf16 v[16:19], v[230:233], v[188:191], v[16:19]
	v_mfma_f32_16x16x32_bf16 v[4:7], v[222:225], v[214:217], v[4:7]
	v_mfma_f32_16x16x32_bf16 v[0:3], v[230:233], v[214:217], v[0:3]
.Lg4_skip3:
	s_setprio 0
	s_add_i32 s5, 0, 0x1a400
	v_add_u32_e32 v164, s5, v151
	s_barrier
	ds_read_b128 v[132:135], v164
	ds_read_b128 v[136:139], v164 offset:1024
	ds_read_b128 v[140:143], v164 offset:2048
	ds_read_b128 v[164:167], v164 offset:3072
	s_add_u32 s2, s2, s20
	s_addc_u32 s3, s3, s21
	s_mov_b32 m0, s48
	v_lshl_add_u64 v[248:249], s[2:3], 0, v[146:147]
	ds_read_b128 v[168:171], v176 offset:41984
	ds_read_b128 v[172:175], v176 offset:43008
	ds_read_b128 v[180:183], v176 offset:44032
	ds_read_b128 v[184:187], v176 offset:45056
	ds_read_b128 v[188:191], v176 offset:46080
	ds_read_b128 v[192:195], v176 offset:47104
	ds_read_b128 v[210:213], v176 offset:48128
	ds_read_b128 v[214:217], v176 offset:49152
	v_lshl_add_u64 v[250:251], s[2:3], 0, v[154:155]
	s_add_i32 s2, 0, 0x1e400
	v_add_u32_e32 v209, s2, v151
	ds_read_b128 v[218:221], v209
	ds_read_b128 v[222:225], v209 offset:1024
	ds_read_b128 v[226:229], v209 offset:2048
	ds_read_b128 v[230:233], v209 offset:3072
	global_load_lds_dwordx4 v[248:249], off
	s_mov_b32 m0, s49
	s_nop 0
	global_load_lds_dwordx4 v[250:251], off
	s_waitcnt vmcnt(8) lgkmcnt(0)
	s_barrier
	s_setprio 1
	v_mfma_f32_16x16x32_bf16 v[114:117], v[132:135], v[168:171], v[114:117]
	v_mfma_f32_16x16x32_bf16 v[126:129], v[140:143], v[168:171], v[126:129]
	v_mfma_f32_16x16x32_bf16 v[110:113], v[132:135], v[180:183], v[110:113]
	v_mfma_f32_16x16x32_bf16 v[106:109], v[140:143], v[180:183], v[106:109]
	v_mfma_f32_16x16x32_bf16 v[94:97], v[132:135], v[188:191], v[94:97]
	v_mfma_f32_16x16x32_bf16 v[90:93], v[140:143], v[188:191], v[90:93]
	v_mfma_f32_16x16x32_bf16 v[78:81], v[132:135], v[210:213], v[78:81]
	v_mfma_f32_16x16x32_bf16 v[74:77], v[140:143], v[210:213], v[74:77]
	v_mfma_f32_16x16x32_bf16 v[114:117], v[136:139], v[172:175], v[114:117]
	v_mfma_f32_16x16x32_bf16 v[126:129], v[164:167], v[172:175], v[126:129]
	v_mfma_f32_16x16x32_bf16 v[110:113], v[136:139], v[184:187], v[110:113]
	v_mfma_f32_16x16x32_bf16 v[106:109], v[164:167], v[184:187], v[106:109]
	v_mfma_f32_16x16x32_bf16 v[94:97], v[136:139], v[192:195], v[94:97]
	v_mfma_f32_16x16x32_bf16 v[90:93], v[164:167], v[192:195], v[90:93]
	v_mfma_f32_16x16x32_bf16 v[78:81], v[136:139], v[214:217], v[78:81]
	v_mfma_f32_16x16x32_bf16 v[74:77], v[164:167], v[214:217], v[74:77]
	s_cmp_eq_u32 s62, 64
	s_cbranch_scc1 .Lg4_skip5
	v_mfma_f32_16x16x32_bf16 v[122:125], v[218:221], v[168:171], v[122:125]
	v_mfma_f32_16x16x32_bf16 v[118:121], v[226:229], v[168:171], v[118:121]
	v_mfma_f32_16x16x32_bf16 v[102:105], v[218:221], v[180:183], v[102:105]
	v_mfma_f32_16x16x32_bf16 v[98:101], v[226:229], v[180:183], v[98:101]
	v_mfma_f32_16x16x32_bf16 v[86:89], v[218:221], v[188:191], v[86:89]
	v_mfma_f32_16x16x32_bf16 v[82:85], v[226:229], v[188:191], v[82:85]
	v_mfma_f32_16x16x32_bf16 v[70:73], v[218:221], v[210:213], v[70:73]
	v_mfma_f32_16x16x32_bf16 v[66:69], v[226:229], v[210:213], v[66:69]
	v_mfma_f32_16x16x32_bf16 v[122:125], v[222:225], v[172:175], v[122:125]
	v_mfma_f32_16x16x32_bf16 v[118:121], v[230:233], v[172:175], v[118:121]
	v_mfma_f32_16x16x32_bf16 v[102:105], v[222:225], v[184:187], v[102:105]
	v_mfma_f32_16x16x32_bf16 v[98:101], v[230:233], v[184:187], v[98:101]
	v_mfma_f32_16x16x32_bf16 v[86:89], v[222:225], v[192:195], v[86:89]
	v_mfma_f32_16x16x32_bf16 v[82:85], v[230:233], v[192:195], v[82:85]
	v_mfma_f32_16x16x32_bf16 v[70:73], v[222:225], v[214:217], v[70:73]
	v_mfma_f32_16x16x32_bf16 v[66:69], v[230:233], v[214:217], v[66:69]
.Lg4_skip5:
	s_setprio 0
	s_barrier
	ds_read_b128 v[168:171], v176 offset:58368
	ds_read_b128 v[172:175], v176 offset:59392
	ds_read_b128 v[180:183], v176 offset:60416
	ds_read_b128 v[184:187], v176 offset:61440
	ds_read_b128 v[188:191], v176 offset:62464
	ds_read_b128 v[192:195], v176 offset:63488
	ds_read_b128 v[210:213], v176 offset:64512
	ds_read_b128 v[214:217], v177 offset:7168
	s_add_i32 s3, s5, s45
	v_lshl_add_u64 v[234:235], v[234:235], 0, s[52:53]
	s_mov_b32 m0, s3
	v_lshl_add_u64 v[236:237], v[236:237], 0, s[52:53]
	global_load_lds_dwordx4 v[234:235], off
	s_add_i32 m0, s3, 0x2000
	v_lshl_add_u64 v[238:239], v[238:239], 0, s[52:53]
	global_load_lds_dwordx4 v[236:237], off
	s_mov_b32 m0, s64
	v_lshl_add_u64 v[240:241], v[240:241], 0, s[52:53]
	global_load_lds_dwordx4 v[238:239], off
	s_mov_b32 m0, s65
	v_lshl_add_u64 v[248:249], v[144:145], 0, s[52:53]
	global_load_lds_dwordx4 v[240:241], off
	s_add_i32 s2, s2, s45
	v_lshl_add_u64 v[250:251], v[242:243], 0, s[52:53]
	s_mov_b32 m0, s2
	s_nop 0
	global_load_lds_dwordx4 v[248:249], off
	s_add_i32 m0, s2, 0x2000
	s_nop 0
	global_load_lds_dwordx4 v[250:251], off
	s_waitcnt vmcnt(8) lgkmcnt(0)
	s_barrier
	s_setprio 1
	v_mfma_f32_16x16x32_bf16 v[62:65], v[132:135], v[168:171], v[62:65]
	v_mfma_f32_16x16x32_bf16 v[58:61], v[140:143], v[168:171], v[58:61]
	v_mfma_f32_16x16x32_bf16 v[46:49], v[132:135], v[180:183], v[46:49]
	v_mfma_f32_16x16x32_bf16 v[42:45], v[140:143], v[180:183], v[42:45]
	v_mfma_f32_16x16x32_bf16 v[30:33], v[132:135], v[188:191], v[30:33]
	v_mfma_f32_16x16x32_bf16 v[24:27], v[140:143], v[188:191], v[24:27]
	v_mfma_f32_16x16x32_bf16 v[12:15], v[132:135], v[210:213], v[12:15]
	v_mfma_f32_16x16x32_bf16 v[8:11], v[140:143], v[210:213], v[8:11]
	v_mfma_f32_16x16x32_bf16 v[62:65], v[136:139], v[172:175], v[62:65]
	v_mfma_f32_16x16x32_bf16 v[58:61], v[164:167], v[172:175], v[58:61]
	v_mfma_f32_16x16x32_bf16 v[46:49], v[136:139], v[184:187], v[46:49]
	v_mfma_f32_16x16x32_bf16 v[42:45], v[164:167], v[184:187], v[42:45]
	v_mfma_f32_16x16x32_bf16 v[30:33], v[136:139], v[192:195], v[30:33]
	v_mfma_f32_16x16x32_bf16 v[24:27], v[164:167], v[192:195], v[24:27]
	v_mfma_f32_16x16x32_bf16 v[12:15], v[136:139], v[214:217], v[12:15]
	v_mfma_f32_16x16x32_bf16 v[8:11], v[164:167], v[214:217], v[8:11]
	s_cmp_eq_u32 s62, 64
	s_cbranch_scc1 .Lg4_skip7
	v_mfma_f32_16x16x32_bf16 v[54:57], v[218:221], v[168:171], v[54:57]
	v_mfma_f32_16x16x32_bf16 v[50:53], v[226:229], v[168:171], v[50:53]
	v_mfma_f32_16x16x32_bf16 v[38:41], v[218:221], v[180:183], v[38:41]
	v_mfma_f32_16x16x32_bf16 v[34:37], v[226:229], v[180:183], v[34:37]
	v_mfma_f32_16x16x32_bf16 v[20:23], v[218:221], v[188:191], v[20:23]
	v_mfma_f32_16x16x32_bf16 v[16:19], v[226:229], v[188:191], v[16:19]
	v_mfma_f32_16x16x32_bf16 v[4:7], v[218:221], v[210:213], v[4:7]
	v_mfma_f32_16x16x32_bf16 v[0:3], v[226:229], v[210:213], v[0:3]
	v_mfma_f32_16x16x32_bf16 v[54:57], v[222:225], v[172:175], v[54:57]
	v_mfma_f32_16x16x32_bf16 v[50:53], v[230:233], v[172:175], v[50:53]
	v_mfma_f32_16x16x32_bf16 v[38:41], v[222:225], v[184:187], v[38:41]
	v_mfma_f32_16x16x32_bf16 v[34:37], v[230:233], v[184:187], v[34:37]
	v_mfma_f32_16x16x32_bf16 v[20:23], v[222:225], v[192:195], v[20:23]
	v_mfma_f32_16x16x32_bf16 v[16:19], v[230:233], v[192:195], v[16:19]
	v_mfma_f32_16x16x32_bf16 v[4:7], v[222:225], v[214:217], v[4:7]
	v_mfma_f32_16x16x32_bf16 v[0:3], v[230:233], v[214:217], v[0:3]
.Lg4_skip7:
	s_setprio 0
	s_add_u32 s0, s0, 0x100
	s_addc_u32 s1, s1, 0
	v_lshl_add_u64 v[130:131], v[130:131], 0, s[96:97]
	s_cmp_ge_i32 s4, s62
	s_mov_b32 s2, s4
	s_barrier
	s_cbranch_scc0 .LBB0_287
